# adds K-loop first-iteration peel: first MFMA of each accumulator uses C=0, removes 128 v_mov zeroing and the vmcnt(0) drain before each tile
# speedup vs baseline: 1.0145x; 1.0121x over previous
.LBB0_293:
	v_readlane_b32 s0, v255, 31
	v_readlane_b32 s1, v255, 32
	s_andn2_b64 vcc, exec, s[0:1]
	s_cbranch_vccnz .LBB0_296
	s_add_u32 s0, s90, 0x80
	s_addc_u32 s1, s91, 0
	s_add_u32 s11, s2, 0x100
	s_addc_u32 s24, s3, 0
	s_mov_b32 s2, 0
	s_add_i32 s90, s2, 2
	s_add_u32 s82, s0, 0x80
	s_addc_u32 s3, s1, 0
	s_add_i32 s83, 0, 0x10000
	s_cmp_eq_u32 s62, s2
	s_cselect_b32 s3, s23, s3
	s_cselect_b32 s2, s22, s82
	s_cselect_b32 vcc_hi, s13, s24
	s_cselect_b32 vcc_lo, s12, s11
	s_add_i32 s82, 0, 0x14000
	v_add_u32_e32 v140, s83, v157
	v_add_u32_e32 v144, s82, v157
	ds_read_b128 v[128:131], v140
	ds_read_b128 v[132:135], v140 offset:1024
	ds_read_b128 v[136:139], v140 offset:2048
	ds_read_b128 v[140:143], v140 offset:3072
	ds_read_b128 v[166:169], v144
	ds_read_b128 v[176:179], v144 offset:1024
	ds_read_b128 v[180:183], v144 offset:2048
	ds_read_b128 v[184:187], v144 offset:3072
	v_lshl_add_u64 v[170:171], s[0:1], 0, v[160:161]
	s_add_i32 m0, s37, 0xc000
	ds_read_b128 v[188:191], v242
	ds_read_b128 v[192:195], v242 offset:1024
	ds_read_b128 v[196:199], v242 offset:2048
	ds_read_b128 v[200:203], v242 offset:3072
	ds_read_b128 v[204:207], v242 offset:4096
	ds_read_b128 v[208:211], v242 offset:5120
	ds_read_b128 v[212:215], v242 offset:6144
	ds_read_b128 v[216:219], v242 offset:7168
	global_load_lds_dwordx4 v[170:171], off
	v_lshl_add_u64 v[170:171], s[0:1], 0, v[162:163]
	s_add_i32 m0, s37, 0xe000
	s_nop 0
	global_load_lds_dwordx4 v[170:171], off
	s_waitcnt vmcnt(8)
	s_waitcnt lgkmcnt(0)
	s_barrier
	s_setprio 1
	s_waitcnt lgkmcnt(0)
	v_mfma_f32_16x16x32_bf16 v[124:127], v[128:131], v[188:191], 0
	v_mfma_f32_16x16x32_bf16 v[120:123], v[136:139], v[188:191], 0
	v_mfma_f32_16x16x32_bf16 v[108:111], v[128:131], v[196:199], 0
	v_mfma_f32_16x16x32_bf16 v[104:107], v[136:139], v[196:199], 0
	v_mfma_f32_16x16x32_bf16 v[92:95], v[128:131], v[204:207], 0
	v_mfma_f32_16x16x32_bf16 v[88:91], v[136:139], v[204:207], 0
	v_mfma_f32_16x16x32_bf16 v[76:79], v[128:131], v[212:215], 0
	v_mfma_f32_16x16x32_bf16 v[72:75], v[136:139], v[212:215], 0
	v_mfma_f32_16x16x32_bf16 v[124:127], v[132:135], v[192:195], v[124:127]
	v_mfma_f32_16x16x32_bf16 v[120:123], v[140:143], v[192:195], v[120:123]
	v_mfma_f32_16x16x32_bf16 v[108:111], v[132:135], v[200:203], v[108:111]
	v_mfma_f32_16x16x32_bf16 v[104:107], v[140:143], v[200:203], v[104:107]
	v_mfma_f32_16x16x32_bf16 v[92:95], v[132:135], v[208:211], v[92:95]
	v_mfma_f32_16x16x32_bf16 v[88:91], v[140:143], v[208:211], v[88:91]
	v_mfma_f32_16x16x32_bf16 v[76:79], v[132:135], v[216:219], v[76:79]
	v_mfma_f32_16x16x32_bf16 v[72:75], v[140:143], v[216:219], v[72:75]
	s_setprio 0
	s_setprio 1
	v_mfma_f32_16x16x32_bf16 v[116:119], v[166:169], v[188:191], 0
	v_mfma_f32_16x16x32_bf16 v[112:115], v[180:183], v[188:191], 0
	v_mfma_f32_16x16x32_bf16 v[100:103], v[166:169], v[196:199], 0
	v_mfma_f32_16x16x32_bf16 v[96:99], v[180:183], v[196:199], 0
	v_mfma_f32_16x16x32_bf16 v[84:87], v[166:169], v[204:207], 0
	v_mfma_f32_16x16x32_bf16 v[80:83], v[180:183], v[204:207], 0
	v_mfma_f32_16x16x32_bf16 v[68:71], v[166:169], v[212:215], 0
	v_mfma_f32_16x16x32_bf16 v[64:67], v[180:183], v[212:215], 0
	v_mfma_f32_16x16x32_bf16 v[116:119], v[176:179], v[192:195], v[116:119]
	v_mfma_f32_16x16x32_bf16 v[112:115], v[184:187], v[192:195], v[112:115]
	v_mfma_f32_16x16x32_bf16 v[100:103], v[176:179], v[200:203], v[100:103]
	v_mfma_f32_16x16x32_bf16 v[96:99], v[184:187], v[200:203], v[96:99]
	v_mfma_f32_16x16x32_bf16 v[84:87], v[176:179], v[208:211], v[84:87]
	v_mfma_f32_16x16x32_bf16 v[80:83], v[184:187], v[208:211], v[80:83]
	v_mfma_f32_16x16x32_bf16 v[68:71], v[176:179], v[216:219], v[68:71]
	v_mfma_f32_16x16x32_bf16 v[64:67], v[184:187], v[216:219], v[64:67]
	s_setprio 0
	s_barrier
	s_add_i32 s83, s83, s36
	v_lshl_add_u64 v[170:171], vcc, 0, v[150:151]
	s_mov_b32 m0, s83
	ds_read_b128 v[188:191], v242 offset:16384
	ds_read_b128 v[192:195], v242 offset:17408
	ds_read_b128 v[196:199], v242 offset:18432
	ds_read_b128 v[200:203], v242 offset:19456
	ds_read_b128 v[204:207], v242 offset:20480
	ds_read_b128 v[208:211], v242 offset:21504
	ds_read_b128 v[212:215], v242 offset:22528
	ds_read_b128 v[216:219], v242 offset:23552
	global_load_lds_dwordx4 v[170:171], off
	s_add_i32 m0, s83, 0x2000
	v_lshl_add_u64 v[232:233], vcc, 0, v[154:155]
	s_add_u32 vcc_lo, vcc_lo, s26
	s_addc_u32 vcc_hi, vcc_hi, 0
	s_add_i32 s82, s82, s36
	global_load_lds_dwordx4 v[232:233], off
	v_lshl_add_u64 v[234:235], vcc, 0, v[150:151]
	s_mov_b32 m0, s82
	v_lshl_add_u64 v[246:247], vcc, 0, v[154:155]
	global_load_lds_dwordx4 v[234:235], off
	s_add_i32 m0, s82, 0x2000
	v_lshl_add_u64 v[248:249], s[2:3], 0, v[148:149]
	global_load_lds_dwordx4 v[246:247], off
	s_mov_b32 m0, s37
	v_lshl_add_u64 v[250:251], s[2:3], 0, v[152:153]
	global_load_lds_dwordx4 v[248:249], off
	s_mov_b32 m0, s42
	s_nop 0
	global_load_lds_dwordx4 v[250:251], off
	s_waitcnt vmcnt(8)
	s_waitcnt lgkmcnt(0)
	s_barrier
	s_setprio 1
	s_waitcnt lgkmcnt(0)
	v_mfma_f32_16x16x32_bf16 v[60:63], v[128:131], v[188:191], 0
	v_mfma_f32_16x16x32_bf16 v[56:59], v[136:139], v[188:191], 0
	v_mfma_f32_16x16x32_bf16 v[44:47], v[128:131], v[196:199], 0
	v_mfma_f32_16x16x32_bf16 v[40:43], v[136:139], v[196:199], 0
	v_mfma_f32_16x16x32_bf16 v[28:31], v[128:131], v[204:207], 0
	v_mfma_f32_16x16x32_bf16 v[24:27], v[136:139], v[204:207], 0
	v_mfma_f32_16x16x32_bf16 v[12:15], v[128:131], v[212:215], 0
	v_mfma_f32_16x16x32_bf16 v[8:11], v[136:139], v[212:215], 0
	v_mfma_f32_16x16x32_bf16 v[60:63], v[132:135], v[192:195], v[60:63]
	v_mfma_f32_16x16x32_bf16 v[56:59], v[140:143], v[192:195], v[56:59]
	v_mfma_f32_16x16x32_bf16 v[44:47], v[132:135], v[200:203], v[44:47]
	v_mfma_f32_16x16x32_bf16 v[40:43], v[140:143], v[200:203], v[40:43]
	v_mfma_f32_16x16x32_bf16 v[28:31], v[132:135], v[208:211], v[28:31]
	v_mfma_f32_16x16x32_bf16 v[24:27], v[140:143], v[208:211], v[24:27]
	v_mfma_f32_16x16x32_bf16 v[12:15], v[132:135], v[216:219], v[12:15]
	v_mfma_f32_16x16x32_bf16 v[8:11], v[140:143], v[216:219], v[8:11]
	s_setprio 0
	s_setprio 1
	v_mfma_f32_16x16x32_bf16 v[52:55], v[166:169], v[188:191], 0
	v_mfma_f32_16x16x32_bf16 v[48:51], v[180:183], v[188:191], 0
	v_mfma_f32_16x16x32_bf16 v[36:39], v[166:169], v[196:199], 0
	v_mfma_f32_16x16x32_bf16 v[32:35], v[180:183], v[196:199], 0
	v_mfma_f32_16x16x32_bf16 v[20:23], v[166:169], v[204:207], 0
	v_mfma_f32_16x16x32_bf16 v[16:19], v[180:183], v[204:207], 0
	v_mfma_f32_16x16x32_bf16 v[4:7], v[166:169], v[212:215], 0
	v_mfma_f32_16x16x32_bf16 v[0:3], v[180:183], v[212:215], 0
	v_mfma_f32_16x16x32_bf16 v[52:55], v[176:179], v[192:195], v[52:55]
	v_mfma_f32_16x16x32_bf16 v[48:51], v[184:187], v[192:195], v[48:51]
	v_mfma_f32_16x16x32_bf16 v[36:39], v[176:179], v[200:203], v[36:39]
	v_mfma_f32_16x16x32_bf16 v[32:35], v[184:187], v[200:203], v[32:35]
	v_mfma_f32_16x16x32_bf16 v[20:23], v[176:179], v[208:211], v[20:23]
	v_mfma_f32_16x16x32_bf16 v[16:19], v[184:187], v[208:211], v[16:19]
	v_mfma_f32_16x16x32_bf16 v[4:7], v[176:179], v[216:219], v[4:7]
	v_mfma_f32_16x16x32_bf16 v[0:3], v[184:187], v[216:219], v[0:3]
	s_setprio 0
	s_barrier
	s_add_i32 s82, 0, 0x18000
	s_add_i32 s83, 0, 0x1c000
	v_add_u32_e32 v140, s82, v157
	v_add_u32_e32 v144, s83, v157
	ds_read_b128 v[128:131], v140
	ds_read_b128 v[132:135], v140 offset:1024
	ds_read_b128 v[136:139], v140 offset:2048
	ds_read_b128 v[140:143], v140 offset:3072
	ds_read_b128 v[166:169], v144
	ds_read_b128 v[176:179], v144 offset:1024
	ds_read_b128 v[180:183], v144 offset:2048
	ds_read_b128 v[184:187], v144 offset:3072
	s_add_u32 s2, s2, s58
	s_addc_u32 s3, s3, 0
	s_mov_b32 m0, s43
	v_lshl_add_u64 v[238:239], s[2:3], 0, v[148:149]
	ds_read_b128 v[188:191], v242 offset:32768
	ds_read_b128 v[192:195], v242 offset:33792
	ds_read_b128 v[196:199], v242 offset:34816
	ds_read_b128 v[200:203], v242 offset:35840
	ds_read_b128 v[204:207], v242 offset:36864
	ds_read_b128 v[208:211], v242 offset:37888
	ds_read_b128 v[212:215], v242 offset:38912
	ds_read_b128 v[216:219], v242 offset:39936
	global_load_lds_dwordx4 v[238:239], off
	v_lshl_add_u64 v[238:239], s[2:3], 0, v[152:153]
	s_mov_b32 m0, s16
	s_nop 0
	global_load_lds_dwordx4 v[238:239], off
	s_waitcnt vmcnt(8)
	s_waitcnt lgkmcnt(0)
	s_barrier
	s_setprio 1
	s_waitcnt lgkmcnt(0)
	v_mfma_f32_16x16x32_bf16 v[124:127], v[128:131], v[188:191], v[124:127]
	v_mfma_f32_16x16x32_bf16 v[120:123], v[136:139], v[188:191], v[120:123]
	v_mfma_f32_16x16x32_bf16 v[108:111], v[128:131], v[196:199], v[108:111]
	v_mfma_f32_16x16x32_bf16 v[104:107], v[136:139], v[196:199], v[104:107]
	v_mfma_f32_16x16x32_bf16 v[92:95], v[128:131], v[204:207], v[92:95]
	v_mfma_f32_16x16x32_bf16 v[88:91], v[136:139], v[204:207], v[88:91]
	v_mfma_f32_16x16x32_bf16 v[76:79], v[128:131], v[212:215], v[76:79]
	v_mfma_f32_16x16x32_bf16 v[72:75], v[136:139], v[212:215], v[72:75]
	v_mfma_f32_16x16x32_bf16 v[124:127], v[132:135], v[192:195], v[124:127]
	v_mfma_f32_16x16x32_bf16 v[120:123], v[140:143], v[192:195], v[120:123]
	v_mfma_f32_16x16x32_bf16 v[108:111], v[132:135], v[200:203], v[108:111]
	v_mfma_f32_16x16x32_bf16 v[104:107], v[140:143], v[200:203], v[104:107]
	v_mfma_f32_16x16x32_bf16 v[92:95], v[132:135], v[208:211], v[92:95]
	v_mfma_f32_16x16x32_bf16 v[88:91], v[140:143], v[208:211], v[88:91]
	v_mfma_f32_16x16x32_bf16 v[76:79], v[132:135], v[216:219], v[76:79]
	v_mfma_f32_16x16x32_bf16 v[72:75], v[140:143], v[216:219], v[72:75]
	s_setprio 0
	s_setprio 1
	v_mfma_f32_16x16x32_bf16 v[116:119], v[166:169], v[188:191], v[116:119]
	v_mfma_f32_16x16x32_bf16 v[112:115], v[180:183], v[188:191], v[112:115]
	v_mfma_f32_16x16x32_bf16 v[100:103], v[166:169], v[196:199], v[100:103]
	v_mfma_f32_16x16x32_bf16 v[96:99], v[180:183], v[196:199], v[96:99]
	v_mfma_f32_16x16x32_bf16 v[84:87], v[166:169], v[204:207], v[84:87]
	v_mfma_f32_16x16x32_bf16 v[80:83], v[180:183], v[204:207], v[80:83]
	v_mfma_f32_16x16x32_bf16 v[68:71], v[166:169], v[212:215], v[68:71]
	v_mfma_f32_16x16x32_bf16 v[64:67], v[180:183], v[212:215], v[64:67]
	v_mfma_f32_16x16x32_bf16 v[116:119], v[176:179], v[192:195], v[116:119]
	v_mfma_f32_16x16x32_bf16 v[112:115], v[184:187], v[192:195], v[112:115]
	v_mfma_f32_16x16x32_bf16 v[100:103], v[176:179], v[200:203], v[100:103]
	v_mfma_f32_16x16x32_bf16 v[96:99], v[184:187], v[200:203], v[96:99]
	v_mfma_f32_16x16x32_bf16 v[84:87], v[176:179], v[208:211], v[84:87]
	v_mfma_f32_16x16x32_bf16 v[80:83], v[184:187], v[208:211], v[80:83]
	v_mfma_f32_16x16x32_bf16 v[68:71], v[176:179], v[216:219], v[68:71]
	v_mfma_f32_16x16x32_bf16 v[64:67], v[184:187], v[216:219], v[64:67]
	s_setprio 0
	s_barrier
	s_add_i32 s2, s82, s36
	v_lshl_add_u64 v[170:171], v[170:171], 0, s[30:31]
	s_mov_b32 m0, s2
	ds_read_b128 v[188:191], v242 offset:49152
	ds_read_b128 v[192:195], v242 offset:50176
	ds_read_b128 v[196:199], v242 offset:51200
	ds_read_b128 v[200:203], v242 offset:52224
	ds_read_b128 v[204:207], v242 offset:53248
	ds_read_b128 v[208:211], v242 offset:54272
	ds_read_b128 v[212:215], v242 offset:55296
	ds_read_b128 v[216:219], v242 offset:56320
	global_load_lds_dwordx4 v[170:171], off
	v_lshl_add_u64 v[170:171], v[232:233], 0, s[30:31]
	s_add_i32 m0, s2, 0x2000
	s_add_i32 s2, s83, s36
	global_load_lds_dwordx4 v[170:171], off
	v_lshl_add_u64 v[170:171], v[234:235], 0, s[30:31]
	s_mov_b32 m0, s2
	s_nop 0
	global_load_lds_dwordx4 v[170:171], off
	v_lshl_add_u64 v[170:171], v[246:247], 0, s[30:31]
	s_add_i32 m0, s2, 0x2000
	s_nop 0
	global_load_lds_dwordx4 v[170:171], off
	v_lshl_add_u64 v[170:171], v[248:249], 0, s[30:31]
	s_mov_b32 m0, s63
	s_nop 0
	global_load_lds_dwordx4 v[170:171], off
	v_lshl_add_u64 v[170:171], v[250:251], 0, s[30:31]
	s_mov_b32 m0, s18
	s_nop 0
	global_load_lds_dwordx4 v[170:171], off
	s_waitcnt vmcnt(8)
	s_waitcnt lgkmcnt(0)
	s_barrier
	s_setprio 1
	s_waitcnt lgkmcnt(0)
	v_mfma_f32_16x16x32_bf16 v[60:63], v[128:131], v[188:191], v[60:63]
	v_mfma_f32_16x16x32_bf16 v[56:59], v[136:139], v[188:191], v[56:59]
	v_mfma_f32_16x16x32_bf16 v[44:47], v[128:131], v[196:199], v[44:47]
	v_mfma_f32_16x16x32_bf16 v[40:43], v[136:139], v[196:199], v[40:43]
	v_mfma_f32_16x16x32_bf16 v[28:31], v[128:131], v[204:207], v[28:31]
	v_mfma_f32_16x16x32_bf16 v[24:27], v[136:139], v[204:207], v[24:27]
	v_mfma_f32_16x16x32_bf16 v[12:15], v[128:131], v[212:215], v[12:15]
	v_mfma_f32_16x16x32_bf16 v[8:11], v[136:139], v[212:215], v[8:11]
	v_mfma_f32_16x16x32_bf16 v[60:63], v[132:135], v[192:195], v[60:63]
	v_mfma_f32_16x16x32_bf16 v[56:59], v[140:143], v[192:195], v[56:59]
	v_mfma_f32_16x16x32_bf16 v[44:47], v[132:135], v[200:203], v[44:47]
	v_mfma_f32_16x16x32_bf16 v[40:43], v[140:143], v[200:203], v[40:43]
	v_mfma_f32_16x16x32_bf16 v[28:31], v[132:135], v[208:211], v[28:31]
	v_mfma_f32_16x16x32_bf16 v[24:27], v[140:143], v[208:211], v[24:27]
	v_mfma_f32_16x16x32_bf16 v[12:15], v[132:135], v[216:219], v[12:15]
	v_mfma_f32_16x16x32_bf16 v[8:11], v[140:143], v[216:219], v[8:11]
	s_setprio 0
	s_setprio 1
	v_mfma_f32_16x16x32_bf16 v[52:55], v[166:169], v[188:191], v[52:55]
	v_mfma_f32_16x16x32_bf16 v[48:51], v[180:183], v[188:191], v[48:51]
	v_mfma_f32_16x16x32_bf16 v[36:39], v[166:169], v[196:199], v[36:39]
	v_mfma_f32_16x16x32_bf16 v[32:35], v[180:183], v[196:199], v[32:35]
	v_mfma_f32_16x16x32_bf16 v[20:23], v[166:169], v[204:207], v[20:23]
	v_mfma_f32_16x16x32_bf16 v[16:19], v[180:183], v[204:207], v[16:19]
	v_mfma_f32_16x16x32_bf16 v[4:7], v[166:169], v[212:215], v[4:7]
	v_mfma_f32_16x16x32_bf16 v[0:3], v[180:183], v[212:215], v[0:3]
	v_mfma_f32_16x16x32_bf16 v[52:55], v[176:179], v[192:195], v[52:55]
	v_mfma_f32_16x16x32_bf16 v[48:51], v[184:187], v[192:195], v[48:51]
	v_mfma_f32_16x16x32_bf16 v[36:39], v[176:179], v[200:203], v[36:39]
	v_mfma_f32_16x16x32_bf16 v[32:35], v[184:187], v[200:203], v[32:35]
	v_mfma_f32_16x16x32_bf16 v[20:23], v[176:179], v[208:211], v[20:23]
	v_mfma_f32_16x16x32_bf16 v[16:19], v[184:187], v[208:211], v[16:19]
	v_mfma_f32_16x16x32_bf16 v[4:7], v[176:179], v[216:219], v[4:7]
	v_mfma_f32_16x16x32_bf16 v[0:3], v[184:187], v[216:219], v[0:3]
	s_setprio 0
	s_barrier
	s_add_u32 s0, s0, 0x100
	s_addc_u32 s1, s1, 0
	s_add_u32 s11, s11, 0x100
	s_addc_u32 s24, s24, 0
	s_cmp_ge_u32 s90, s60
	s_mov_b32 s2, s90
	s_cbranch_scc1 .LBB0_297
